# grid barrier leader: buffer_inv issued right behind buffer_wbl2 (one wait for both) instead of after the write-back retired
# speedup vs baseline: 1.0175x; 1.0012x over previous
.LBB0_149:
	s_andn2_saveexec_b64 s[8:9], s[8:9]
	s_cbranch_execz .LBB0_169
	s_mov_b64 s[8:9], exec
	buffer_wbl2 sc1
	buffer_inv sc1
	s_waitcnt lgkmcnt(0)
	s_waitcnt vmcnt(0)
	v_mbcnt_lo_u32_b32 v1, s8, 0
	v_mbcnt_hi_u32_b32 v1, s9, v1
	v_cmp_eq_u32_e32 vcc, 0, v1
	s_and_saveexec_b64 s[12:13], vcc
	s_cbranch_execz .LBB0_152
	s_bcnt1_i32_b64 s8, s[8:9]
	v_mov_b32_e32 v2, 0xf201000
	v_mov_b32_e32 v3, s8
	global_atomic_add v2, v2, v3, s[92:93] offset:1024 sc0

.LBB0_226:
	s_andn2_saveexec_b64 s[6:7], s[6:7]
	s_cbranch_execz .LBB0_246
	s_mov_b64 s[6:7], exec
	buffer_wbl2 sc1
	buffer_inv sc1
	s_waitcnt lgkmcnt(0)
	s_waitcnt vmcnt(0)
	v_mbcnt_lo_u32_b32 v1, s6, 0
	v_mbcnt_hi_u32_b32 v1, s7, v1
	v_cmp_eq_u32_e32 vcc, 0, v1
	s_and_saveexec_b64 s[8:9], vcc
	s_cbranch_execz .LBB0_229
	s_bcnt1_i32_b64 s6, s[6:7]
	v_mov_b32_e32 v2, 0xf201000
	v_mov_b32_e32 v3, s6
	global_atomic_add v2, v2, v3, s[92:93] offset:1024 sc0

.LBB0_315:
	s_andn2_saveexec_b64 s[4:5], s[10:11]
	s_cbranch_execz .LBB0_335
	s_mov_b64 s[10:11], exec
	buffer_wbl2 sc1
	buffer_inv sc1
	s_waitcnt lgkmcnt(0)
	s_waitcnt vmcnt(0)
	v_mbcnt_lo_u32_b32 v1, s10, 0
	v_mbcnt_hi_u32_b32 v1, s11, v1
	v_cmp_eq_u32_e32 vcc, 0, v1
	s_and_saveexec_b64 s[16:17], vcc
	s_cbranch_execz .LBB0_318
	s_bcnt1_i32_b64 s4, s[10:11]
	v_mov_b32_e32 v2, s4
	v_readlane_b32 s4, v254, 14
	v_readlane_b32 s5, v254, 15
	s_nop 4
	global_atomic_add v2, v193, v2, s[4:5] sc0

.LBB0_516:
	s_andn2_saveexec_b64 s[10:11], s[10:11]
	s_cbranch_execz .LBB0_536
	s_mov_b64 s[10:11], exec
	buffer_wbl2 sc1
	buffer_inv sc1
	s_waitcnt lgkmcnt(0)
	s_waitcnt vmcnt(0)
	v_mbcnt_lo_u32_b32 v1, s10, 0
	v_mbcnt_hi_u32_b32 v1, s11, v1
	v_cmp_eq_u32_e32 vcc, 0, v1
	s_and_saveexec_b64 s[16:17], vcc
	s_cbranch_execz .LBB0_519
	s_bcnt1_i32_b64 s5, s[10:11]
	v_readlane_b32 s10, v254, 14
	v_mov_b32_e32 v2, s5
	v_readlane_b32 s11, v254, 15
	s_nop 4
	global_atomic_add v2, v193, v2, s[10:11] sc0
